# attention: software-pipelined iteration body for unmasked tiles (QK of 2nd sub-tile and PV of 1st overlap the softmax VALU), on top of v76
# speedup vs baseline: 1.0029x; 1.0000x over previous
.LBB0_509:
	s_or_b64 exec, exec, s[4:5]
	v_add_u32_e32 v65, s12, v190
	v_mov_b32_e32 v70, s33
	v_cmp_lt_i32_e32 vcc, 15, v65
	v_min_i32_e32 v64, 0x80f, v65
	s_and_b32 s89, 1, s64
	v_cndmask_b32_e32 v65, v179, v70, vcc
	v_add_u32_e32 v66, v65, v64
	v_ashrrev_i32_e32 v67, 31, v66
	v_lshlrev_b64 v[66:67], 14, v[66:67]
	v_lshl_add_u64 v[66:67], v[160:161], 0, v[66:67]
	v_add_co_u32_e32 v68, vcc, s65, v66
	v_ashrrev_i32_e32 v65, 31, v64
	s_nop 0
	v_addc_co_u32_e32 v69, vcc, 0, v67, vcc
	v_add_co_u32_e32 v66, vcc, s63, v66
	v_lshl_add_u64 v[64:65], v[64:65], 2, s[54:55]
	s_nop 0
	v_addc_co_u32_e32 v67, vcc, 0, v67, vcc
	global_load_dwordx4 v[130:133], v[68:69], off offset:2048
	global_load_dwordx4 v[116:119], v[66:67], off
	v_add_u32_e32 v67, s12, v189
	v_cmp_lt_i32_e32 vcc, 15, v67
	v_min_i32_e32 v66, 0x80f, v67
	s_cselect_b32 s4, 0, 0x8a00
	v_cndmask_b32_e32 v67, v179, v70, vcc
	v_add_u32_e32 v68, v67, v66
	v_ashrrev_i32_e32 v69, 31, v68
	v_lshlrev_b64 v[68:69], 14, v[68:69]
	v_lshl_add_u64 v[68:69], v[160:161], 0, v[68:69]
	v_add_co_u32_e32 v70, vcc, 0x2000, v68
	v_ashrrev_i32_e32 v67, 31, v66
	s_nop 0
	v_addc_co_u32_e32 v71, vcc, 0, v69, vcc
	global_load_dword v168, v[64:65], off
	global_load_dwordx4 v[120:123], v[70:71], off offset:2048
	v_add_co_u32_e32 v64, vcc, 0x3000, v68
	v_lshl_add_u64 v[66:67], v[66:67], 2, s[54:55]
	s_nop 0
	v_addc_co_u32_e32 v65, vcc, 0, v69, vcc
	global_load_dwordx4 v[124:127], v[64:65], off
	global_load_dword v166, v[66:67], off
	s_add_i32 s4, s4, 0
	v_add_u32_e32 v193, s4, v162
	v_add_u32_e32 v64, s4, v177
	v_add_u32_e32 v191, s4, v247
	s_add_i32 s5, s12, 63
	s_cmp_le_i32 s5, s15
	s_cbranch_scc1 .Lswp
	s_add_i32 s4, s12, 32
	s_cmp_gt_i32 s4, s82
	s_cbranch_scc1 .LBB0_530
	v_add_u32_e32 v68, v193, v176
	ds_read_b128 v[64:67], v68
	ds_read_b128 v[134:137], v68 offset:32
	ds_read_b128 v[138:141], v68 offset:64
	ds_read_b128 v[142:145], v68 offset:96
	ds_read_b128 v[150:153], v68 offset:128
	ds_read_b128 v[170:173], v68 offset:160
	ds_read_b128 v[194:197], v68 offset:192
	ds_read_b128 v[198:201], v68 offset:224
	s_waitcnt lgkmcnt(7)
	v_mfma_f32_32x32x16_bf16 v[64:79], v[64:67], v[80:83], 0
	s_add_i32 s4, s12, 63
	s_cmp_le_i32 s4, s15
	s_cselect_b64 s[56:57], -1, 0
	s_cmp_gt_i32 s4, s15
	s_mov_b64 s[4:5], -1
	s_waitcnt lgkmcnt(6)
	v_mfma_f32_32x32x16_bf16 v[64:79], v[134:137], v[84:87], v[64:79]
	s_waitcnt lgkmcnt(5)
	v_mfma_f32_32x32x16_bf16 v[64:79], v[138:141], v[88:91], v[64:79]
	s_waitcnt lgkmcnt(4)
	v_mfma_f32_32x32x16_bf16 v[64:79], v[142:145], v[92:95], v[64:79]
	ds_read_b64_tr_b16 v[146:147], v191 offset:25600
	ds_read_b64_tr_b16 v[148:149], v191 offset:27648
	ds_read_b64_tr_b16 v[142:143], v191 offset:29696
	ds_read_b64_tr_b16 v[144:145], v191 offset:31744
	ds_read_b64_tr_b16 v[138:139], v191 offset:26112
	ds_read_b64_tr_b16 v[140:141], v191 offset:28160
	ds_read_b64_tr_b16 v[134:135], v191 offset:30208
	ds_read_b64_tr_b16 v[136:137], v191 offset:32256
	s_waitcnt lgkmcnt(11)
	v_mfma_f32_32x32x16_bf16 v[64:79], v[150:153], v[96:99], v[64:79]
	ds_read_b128 v[150:153], v193 offset:34944
	s_waitcnt lgkmcnt(11)
	v_mfma_f32_32x32x16_bf16 v[64:79], v[170:173], v[100:103], v[64:79]
	s_waitcnt lgkmcnt(0)
	v_xor_b32_e32 v173, 0x80000000, v152
	v_mfma_f32_32x32x16_bf16 v[64:79], v[194:197], v[104:107], v[64:79]
	v_mfma_f32_32x32x16_bf16 v[64:79], v[198:201], v[108:111], v[64:79]
	s_nop 11
	v_sub_f32_e32 v195, v64, v150
	s_cbranch_scc1 .LBB0_512
	v_mov_b32_e32 v170, v65
	v_mov_b32_e32 v171, v66
	v_xor_b32_e32 v172, 0x80000000, v151
	v_pk_add_f32 v[170:171], v[170:171], v[172:173]
	v_sub_f32_e32 v172, v67, v153
	v_max3_f32 v64, v195, s87, v170
	v_max3_f32 v196, v64, v171, v172
	ds_read_b128 v[64:67], v193 offset:34976
	s_waitcnt lgkmcnt(0)
	v_xor_b32_e32 v67, 0x80000000, v67
	v_xor_b32_e32 v66, 0x80000000, v66
	v_pk_add_f32 v[150:151], v[68:69], v[64:65] neg_lo:[0,1] neg_hi:[0,1]
	v_pk_add_f32 v[152:153], v[70:71], v[66:67]
	v_max3_f32 v173, v196, v150, v151
	v_max3_f32 v173, v173, v152, v153
	ds_read_b128 v[64:67], v193 offset:35008
	s_waitcnt lgkmcnt(0)
	v_xor_b32_e32 v67, 0x80000000, v67
	v_xor_b32_e32 v66, 0x80000000, v66
	v_pk_add_f32 v[68:69], v[72:73], v[64:65] neg_lo:[0,1] neg_hi:[0,1]
	v_pk_add_f32 v[70:71], v[74:75], v[66:67]
	v_max3_f32 v196, v173, v68, v69
	v_max3_f32 v196, v196, v70, v71
	ds_read_b128 v[64:67], v193 offset:35040
	s_waitcnt lgkmcnt(0)
	v_xor_b32_e32 v75, 0x80000000, v67
	v_xor_b32_e32 v74, 0x80000000, v66
	v_pk_add_f32 v[72:73], v[76:77], v[64:65] neg_lo:[0,1] neg_hi:[0,1]
	v_pk_add_f32 v[66:67], v[78:79], v[74:75]
	v_max3_f32 v173, v196, v72, v73
	v_max3_f32 v173, v173, v66, v67

.Lswp:
	v_add_u32_e32 v195, v193, v176
	v_add_u32_e32 v249, v193, v169
	ds_read_b128 v[220:223], v195 offset:0
	ds_read_b128 v[224:227], v195 offset:32
	ds_read_b128 v[228:231], v195 offset:64
	ds_read_b128 v[232:235], v195 offset:96
	ds_read_b128 v[236:239], v195 offset:128
	ds_read_b128 v[240:243], v195 offset:160
	ds_read_b128 v[250:253], v195 offset:192
	ds_read_b128 v[134:137], v195 offset:224
	s_waitcnt lgkmcnt(7)
	v_mfma_f32_32x32x16_bf16 v[64:79], v[220:223], v[80:83], 0
	ds_read_b128 v[138:141], v249 offset:0
	ds_read_b128 v[142:145], v249 offset:32
	s_waitcnt lgkmcnt(8)
	v_mfma_f32_32x32x16_bf16 v[64:79], v[224:227], v[84:87], v[64:79]
	ds_read_b128 v[146:149], v249 offset:64
	ds_read_b128 v[150:153], v249 offset:96
	s_waitcnt lgkmcnt(9)
	v_mfma_f32_32x32x16_bf16 v[64:79], v[228:231], v[88:91], v[64:79]
	ds_read_b128 v[220:223], v249 offset:128
	ds_read_b128 v[224:227], v249 offset:160
	s_waitcnt lgkmcnt(10)
	v_mfma_f32_32x32x16_bf16 v[64:79], v[232:235], v[92:95], v[64:79]
	ds_read_b128 v[228:231], v249 offset:192
	ds_read_b128 v[232:235], v249 offset:224
	s_waitcnt lgkmcnt(11)
	v_mfma_f32_32x32x16_bf16 v[64:79], v[236:239], v[96:99], v[64:79]
	ds_read_b128 v[170:173], v193 offset:34944
	ds_read_b128 v[196:199], v193 offset:34976
	s_waitcnt lgkmcnt(12)
	v_mfma_f32_32x32x16_bf16 v[64:79], v[240:243], v[100:103], v[64:79]
	ds_read_b128 v[200:203], v193 offset:35008
	ds_read_b128 v[236:239], v193 offset:35040
	s_waitcnt lgkmcnt(13)
	v_mfma_f32_32x32x16_bf16 v[64:79], v[250:253], v[104:107], v[64:79]
	ds_read_b64_tr_b16 v[240:241], v191 offset:25600
	ds_read_b64_tr_b16 v[242:243], v191 offset:27648
	s_waitcnt lgkmcnt(14)
	v_mfma_f32_32x32x16_bf16 v[64:79], v[134:137], v[108:111], v[64:79]
	ds_read_b64_tr_b16 v[250:251], v191 offset:26112
	s_waitcnt lgkmcnt(14)
	ds_read_b64_tr_b16 v[252:253], v191 offset:28160
	v_mfma_f32_32x32x16_bf16 v[204:219], v[138:141], v[80:83], 0
	s_waitcnt lgkmcnt(14)
	ds_read_b64_tr_b16 v[134:135], v191 offset:26624
	s_waitcnt lgkmcnt(14)
	ds_read_b64_tr_b16 v[136:137], v191 offset:28672
	v_mfma_f32_32x32x16_bf16 v[204:219], v[142:145], v[84:87], v[204:219]
	s_waitcnt lgkmcnt(14)
	ds_read_b64_tr_b16 v[138:139], v191 offset:27136
	s_waitcnt lgkmcnt(14)
	ds_read_b64_tr_b16 v[140:141], v191 offset:29184
	s_waitcnt lgkmcnt(14)
	ds_read_b64_tr_b16 v[142:143], v191 offset:29696
	s_waitcnt lgkmcnt(14)
	ds_read_b64_tr_b16 v[144:145], v191 offset:31744
	s_waitcnt lgkmcnt(13)
	s_nop 1
	v_pk_add_f32 v[64:65], v[64:65], v[170:171] neg_lo:[0,1] neg_hi:[0,1]
	v_pk_add_f32 v[66:67], v[66:67], v[172:173] neg_lo:[0,1] neg_hi:[0,1]
	s_waitcnt lgkmcnt(12)
	v_pk_add_f32 v[68:69], v[68:69], v[196:197] neg_lo:[0,1] neg_hi:[0,1]
	v_pk_add_f32 v[70:71], v[70:71], v[198:199] neg_lo:[0,1] neg_hi:[0,1]
	s_waitcnt lgkmcnt(11)
	v_pk_add_f32 v[72:73], v[72:73], v[200:201] neg_lo:[0,1] neg_hi:[0,1]
	v_pk_add_f32 v[74:75], v[74:75], v[202:203] neg_lo:[0,1] neg_hi:[0,1]
	s_waitcnt lgkmcnt(10)
	v_pk_add_f32 v[76:77], v[76:77], v[236:237] neg_lo:[0,1] neg_hi:[0,1]
	v_pk_add_f32 v[78:79], v[78:79], v[238:239] neg_lo:[0,1] neg_hi:[0,1]
	v_mfma_f32_32x32x16_bf16 v[204:219], v[146:149], v[88:91], v[204:219]
	ds_read_b64_tr_b16 v[146:147], v191 offset:30208
	ds_read_b64_tr_b16 v[148:149], v191 offset:32256
	ds_read_b128 v[170:173], v193 offset:34816
	ds_read_b128 v[196:199], v193 offset:34848
	ds_read_b128 v[200:203], v193 offset:34880
	s_waitcnt lgkmcnt(14)
	ds_read_b128 v[236:239], v193 offset:34912
	v_max3_f32 v254, v64, s87, v65
	v_max3_f32 v254, v254, v66, v67
	v_max3_f32 v254, v254, v68, v69
	v_max3_f32 v254, v254, v70, v71
	v_max3_f32 v254, v254, v72, v73
	v_max3_f32 v254, v254, v74, v75
	v_max3_f32 v254, v254, v76, v77
	v_max3_f32 v254, v254, v78, v79
	v_mfma_f32_32x32x16_bf16 v[204:219], v[150:153], v[92:95], v[204:219]
	s_waitcnt lgkmcnt(14)
	ds_read_b64_tr_b16 v[150:151], v191 offset:30720
	s_waitcnt lgkmcnt(14)
	ds_read_b64_tr_b16 v[152:153], v191 offset:32768
	v_mov_b32_e32 v255, v254
	s_nop 1
	v_permlane32_swap_b32_e32 v254, v255
	v_max_f32_e32 v255, v255, v255
	v_max_f32_e32 v254, v254, v254
	v_max_f32_e32 v255, v254, v255
	v_max_f32_e32 v249, v192, v192
	v_max_f32_e32 v194, v249, v255
	v_cmp_neq_f32_e64 s[4:5], s87, v194
	v_cmp_gt_f32_e32 vcc, v255, v192
	s_nop 0
	v_cndmask_b32_e64 v244, 0, v194, s[4:5]
	s_cbranch_vccnz .LswpA_resc
.LswpA_back:
	v_pk_add_f32 v[64:65], v[64:65], v[244:245] op_sel_hi:[1,0] neg_lo:[0,1] neg_hi:[0,1]
	v_mfma_f32_32x32x16_bf16 v[204:219], v[220:223], v[96:99], v[204:219]
	s_waitcnt lgkmcnt(14)
	ds_read_b64_tr_b16 v[220:221], v191 offset:31232
	s_waitcnt lgkmcnt(14)
	ds_read_b64_tr_b16 v[222:223], v191 offset:33280
	v_pk_add_f32 v[66:67], v[66:67], v[244:245] op_sel_hi:[1,0] neg_lo:[0,1] neg_hi:[0,1]
	v_pk_add_f32 v[68:69], v[68:69], v[244:245] op_sel_hi:[1,0] neg_lo:[0,1] neg_hi:[0,1]
	v_pk_add_f32 v[70:71], v[70:71], v[244:245] op_sel_hi:[1,0] neg_lo:[0,1] neg_hi:[0,1]
	v_pk_add_f32 v[72:73], v[72:73], v[244:245] op_sel_hi:[1,0] neg_lo:[0,1] neg_hi:[0,1]
	v_pk_add_f32 v[74:75], v[74:75], v[244:245] op_sel_hi:[1,0] neg_lo:[0,1] neg_hi:[0,1]
	v_pk_add_f32 v[76:77], v[76:77], v[244:245] op_sel_hi:[1,0] neg_lo:[0,1] neg_hi:[0,1]
	v_pk_add_f32 v[78:79], v[78:79], v[244:245] op_sel_hi:[1,0] neg_lo:[0,1] neg_hi:[0,1]
	v_exp_f32_e32 v64, v64
	v_mfma_f32_32x32x16_bf16 v[204:219], v[224:227], v[100:103], v[204:219]
	v_exp_f32_e32 v65, v65
	v_exp_f32_e32 v66, v66
	v_exp_f32_e32 v67, v67
	v_exp_f32_e32 v68, v68
	v_mfma_f32_32x32x16_bf16 v[204:219], v[228:231], v[104:107], v[204:219]
	v_exp_f32_e32 v69, v69
	v_exp_f32_e32 v70, v70
	v_exp_f32_e32 v71, v71
	v_cvt_pk_bf16_f32 v224, v64, v65
	v_mfma_f32_32x32x16_bf16 v[204:219], v[232:235], v[108:111], v[204:219]
	s_waitcnt lgkmcnt(14)
	ds_read_b64_tr_b16 v[232:233], v191 offset:17408
	s_waitcnt lgkmcnt(14)
	ds_read_b64_tr_b16 v[234:235], v191 offset:19456
	v_cvt_pk_bf16_f32 v225, v66, v67
	v_cvt_pk_bf16_f32 v226, v68, v69
	v_cvt_pk_bf16_f32 v227, v70, v71
	v_exp_f32_e32 v72, v72
	v_exp_f32_e32 v73, v73
	v_exp_f32_e32 v74, v74
	v_exp_f32_e32 v75, v75
	v_exp_f32_e32 v76, v76
	v_exp_f32_e32 v77, v77
	v_exp_f32_e32 v78, v78
	v_exp_f32_e32 v79, v79
	v_cvt_pk_bf16_f32 v228, v72, v73
	v_cvt_pk_bf16_f32 v229, v74, v75
	v_cvt_pk_bf16_f32 v230, v76, v77
	v_cvt_pk_bf16_f32 v231, v78, v79
	v_mfma_f32_32x32x16_bf16 v[48:63], v[240:243], v[224:227], v[48:63]
	v_add_f32_e32 v195, v64, v65
	v_add_f32_e32 v195, v66, v195
	v_add_f32_e32 v195, v67, v195
	v_add_f32_e32 v195, v68, v195
	v_add_f32_e32 v195, v69, v195
	v_add_f32_e32 v195, v70, v195
	v_add_f32_e32 v195, v71, v195
	v_add_f32_e32 v195, v72, v195
	v_mfma_f32_32x32x16_bf16 v[32:47], v[250:253], v[224:227], v[32:47]
	v_add_f32_e32 v195, v73, v195
	v_add_f32_e32 v195, v74, v195
	v_add_f32_e32 v195, v75, v195
	v_add_f32_e32 v195, v76, v195
	v_add_f32_e32 v195, v77, v195
	v_add_f32_e32 v195, v78, v195
	v_add_f32_e32 v195, v79, v195
	v_add_f32_e32 v167, v195, v167
	v_mfma_f32_32x32x16_bf16 v[16:31], v[134:137], v[224:227], v[16:31]
	s_waitcnt lgkmcnt(14)
	ds_read_b64_tr_b16 v[64:65], v191 offset:17920
	s_waitcnt lgkmcnt(14)
	ds_read_b64_tr_b16 v[66:67], v191 offset:19968
	s_waitcnt lgkmcnt(14)
	ds_read_b64_tr_b16 v[68:69], v191 offset:18432
	s_waitcnt lgkmcnt(14)
	ds_read_b64_tr_b16 v[70:71], v191 offset:20480
	s_waitcnt lgkmcnt(14)
	ds_read_b64_tr_b16 v[72:73], v191 offset:18944
	s_waitcnt lgkmcnt(14)
	ds_read_b64_tr_b16 v[74:75], v191 offset:20992
	v_pk_add_f32 v[204:205], v[204:205], v[170:171] neg_lo:[0,1] neg_hi:[0,1]
	v_pk_add_f32 v[206:207], v[206:207], v[172:173] neg_lo:[0,1] neg_hi:[0,1]
	s_waitcnt lgkmcnt(14)
	v_pk_add_f32 v[208:209], v[208:209], v[196:197] neg_lo:[0,1] neg_hi:[0,1]
	v_pk_add_f32 v[210:211], v[210:211], v[198:199] neg_lo:[0,1] neg_hi:[0,1]
	s_waitcnt lgkmcnt(13)
	v_pk_add_f32 v[212:213], v[212:213], v[200:201] neg_lo:[0,1] neg_hi:[0,1]
	v_pk_add_f32 v[214:215], v[214:215], v[202:203] neg_lo:[0,1] neg_hi:[0,1]
	s_waitcnt lgkmcnt(12)
	v_pk_add_f32 v[216:217], v[216:217], v[236:237] neg_lo:[0,1] neg_hi:[0,1]
	v_pk_add_f32 v[218:219], v[218:219], v[238:239] neg_lo:[0,1] neg_hi:[0,1]
	v_mfma_f32_32x32x16_bf16 v[0:15], v[138:141], v[224:227], v[0:15]
	ds_read_b64_tr_b16 v[76:77], v191 offset:21504
	ds_read_b64_tr_b16 v[78:79], v191 offset:23552
	v_max3_f32 v254, v204, s87, v205
	v_max3_f32 v254, v254, v206, v207
	v_max3_f32 v254, v254, v208, v209
	v_max3_f32 v254, v254, v210, v211
	v_max3_f32 v254, v254, v212, v213
	v_max3_f32 v254, v254, v214, v215
	v_max3_f32 v254, v254, v216, v217
	v_max3_f32 v254, v254, v218, v219
	v_mfma_f32_32x32x16_bf16 v[48:63], v[142:145], v[228:231], v[48:63]
	ds_read_b64_tr_b16 v[240:241], v191 offset:22016
	s_waitcnt lgkmcnt(14)
	ds_read_b64_tr_b16 v[242:243], v191 offset:24064
	v_mov_b32_e32 v255, v254
	s_nop 1
	v_permlane32_swap_b32_e32 v254, v255
	v_max_f32_e32 v255, v255, v255
	v_max_f32_e32 v254, v254, v254
	v_max_f32_e32 v255, v254, v255
	v_max_f32_e32 v249, v194, v194
	v_max_f32_e32 v192, v249, v255
	v_cmp_neq_f32_e64 s[4:5], s87, v192
	v_cmp_gt_f32_e64 s[56:57], v255, v194
	s_nop 0
	v_cndmask_b32_e64 v244, 0, v192, s[4:5]
	v_pk_add_f32 v[204:205], v[204:205], v[244:245] op_sel_hi:[1,0] neg_lo:[0,1] neg_hi:[0,1]
	v_mfma_f32_32x32x16_bf16 v[32:47], v[146:149], v[228:231], v[32:47]
	s_waitcnt lgkmcnt(14)
	ds_read_b64_tr_b16 v[250:251], v191 offset:22528
	s_waitcnt lgkmcnt(14)
	ds_read_b64_tr_b16 v[252:253], v191 offset:24576
	v_pk_add_f32 v[206:207], v[206:207], v[244:245] op_sel_hi:[1,0] neg_lo:[0,1] neg_hi:[0,1]
	v_pk_add_f32 v[208:209], v[208:209], v[244:245] op_sel_hi:[1,0] neg_lo:[0,1] neg_hi:[0,1]
	v_pk_add_f32 v[210:211], v[210:211], v[244:245] op_sel_hi:[1,0] neg_lo:[0,1] neg_hi:[0,1]
	v_pk_add_f32 v[212:213], v[212:213], v[244:245] op_sel_hi:[1,0] neg_lo:[0,1] neg_hi:[0,1]
	v_pk_add_f32 v[214:215], v[214:215], v[244:245] op_sel_hi:[1,0] neg_lo:[0,1] neg_hi:[0,1]
	v_pk_add_f32 v[216:217], v[216:217], v[244:245] op_sel_hi:[1,0] neg_lo:[0,1] neg_hi:[0,1]
	v_pk_add_f32 v[218:219], v[218:219], v[244:245] op_sel_hi:[1,0] neg_lo:[0,1] neg_hi:[0,1]
	v_exp_f32_e32 v204, v204
	v_mfma_f32_32x32x16_bf16 v[16:31], v[150:153], v[228:231], v[16:31]
	s_waitcnt lgkmcnt(14)
	ds_read_b64_tr_b16 v[134:135], v191 offset:23040
	s_waitcnt lgkmcnt(14)
	ds_read_b64_tr_b16 v[136:137], v191 offset:25088
	v_exp_f32_e32 v205, v205
	v_exp_f32_e32 v206, v206
	v_exp_f32_e32 v207, v207
	v_exp_f32_e32 v208, v208
	v_exp_f32_e32 v209, v209
	v_exp_f32_e32 v210, v210
	v_exp_f32_e32 v211, v211
	v_cvt_pk_bf16_f32 v170, v204, v205
	v_mfma_f32_32x32x16_bf16 v[0:15], v[220:223], v[228:231], v[0:15]
	v_cvt_pk_bf16_f32 v171, v206, v207
	v_cvt_pk_bf16_f32 v172, v208, v209
	v_cvt_pk_bf16_f32 v173, v210, v211
	v_exp_f32_e32 v212, v212
	v_exp_f32_e32 v213, v213
	v_exp_f32_e32 v214, v214
	v_exp_f32_e32 v215, v215
	v_exp_f32_e32 v216, v216
	v_exp_f32_e32 v217, v217
	v_exp_f32_e32 v218, v218
	v_exp_f32_e32 v219, v219
	v_cvt_pk_bf16_f32 v196, v212, v213
	v_cvt_pk_bf16_f32 v197, v214, v215
	v_cvt_pk_bf16_f32 v198, v216, v217
	v_cvt_pk_bf16_f32 v199, v218, v219
	s_cmp_lg_u64 s[56:57], 0
	s_cbranch_scc1 .LswpB_resc
.LswpB_back:
	s_waitcnt lgkmcnt(14)
	v_mfma_f32_32x32x16_bf16 v[48:63], v[232:235], v[170:173], v[48:63]
	v_add_f32_e32 v195, v204, v205
	v_add_f32_e32 v195, v206, v195
	v_add_f32_e32 v195, v207, v195
	s_waitcnt lgkmcnt(12)
	v_mfma_f32_32x32x16_bf16 v[32:47], v[64:67], v[170:173], v[32:47]
	v_add_f32_e32 v195, v208, v195
	v_add_f32_e32 v195, v209, v195
	v_add_f32_e32 v195, v210, v195
	s_waitcnt lgkmcnt(10)
	v_mfma_f32_32x32x16_bf16 v[16:31], v[68:71], v[170:173], v[16:31]
	v_add_f32_e32 v195, v211, v195
	v_add_f32_e32 v195, v212, v195
	v_add_f32_e32 v195, v213, v195
	s_waitcnt lgkmcnt(8)
	v_mfma_f32_32x32x16_bf16 v[0:15], v[72:75], v[170:173], v[0:15]
	v_add_f32_e32 v195, v214, v195
	v_add_f32_e32 v195, v215, v195
	v_add_f32_e32 v195, v216, v195
	s_waitcnt lgkmcnt(6)
	v_mfma_f32_32x32x16_bf16 v[48:63], v[76:79], v[196:199], v[48:63]
	v_add_f32_e32 v195, v217, v195
	v_add_f32_e32 v195, v218, v195
	s_waitcnt lgkmcnt(4)
	v_mfma_f32_32x32x16_bf16 v[32:47], v[240:243], v[196:199], v[32:47]
	v_add_f32_e32 v195, v219, v195
	v_add_f32_e32 v167, v195, v167
	s_waitcnt lgkmcnt(2)
	v_mfma_f32_32x32x16_bf16 v[16:31], v[250:253], v[196:199], v[16:31]
	s_waitcnt lgkmcnt(0)
	v_mfma_f32_32x32x16_bf16 v[0:15], v[134:137], v[196:199], v[0:15]
	s_branch .LBB0_550
.LswpA_resc:
	v_sub_f32_e32 v254, v192, v244
	v_exp_f32_e32 v254, v254
	s_nop 0
	v_pk_mul_f32 v[62:63], v[62:63], v[254:255] op_sel_hi:[1,0]
	v_pk_mul_f32 v[60:61], v[60:61], v[254:255] op_sel_hi:[1,0]
	v_pk_mul_f32 v[58:59], v[58:59], v[254:255] op_sel_hi:[1,0]
	v_pk_mul_f32 v[56:57], v[56:57], v[254:255] op_sel_hi:[1,0]
	v_pk_mul_f32 v[54:55], v[54:55], v[254:255] op_sel_hi:[1,0]
	v_pk_mul_f32 v[52:53], v[52:53], v[254:255] op_sel_hi:[1,0]
	v_pk_mul_f32 v[50:51], v[50:51], v[254:255] op_sel_hi:[1,0]
	v_pk_mul_f32 v[48:49], v[48:49], v[254:255] op_sel_hi:[1,0]
	v_pk_mul_f32 v[46:47], v[46:47], v[254:255] op_sel_hi:[1,0]
	v_pk_mul_f32 v[44:45], v[44:45], v[254:255] op_sel_hi:[1,0]
	v_pk_mul_f32 v[42:43], v[42:43], v[254:255] op_sel_hi:[1,0]
	v_pk_mul_f32 v[40:41], v[40:41], v[254:255] op_sel_hi:[1,0]
	v_pk_mul_f32 v[38:39], v[38:39], v[254:255] op_sel_hi:[1,0]
	v_pk_mul_f32 v[36:37], v[36:37], v[254:255] op_sel_hi:[1,0]
	v_pk_mul_f32 v[34:35], v[34:35], v[254:255] op_sel_hi:[1,0]
	v_pk_mul_f32 v[32:33], v[32:33], v[254:255] op_sel_hi:[1,0]
	v_pk_mul_f32 v[30:31], v[30:31], v[254:255] op_sel_hi:[1,0]
	v_pk_mul_f32 v[28:29], v[28:29], v[254:255] op_sel_hi:[1,0]
	v_pk_mul_f32 v[26:27], v[26:27], v[254:255] op_sel_hi:[1,0]
	v_pk_mul_f32 v[24:25], v[24:25], v[254:255] op_sel_hi:[1,0]
	v_pk_mul_f32 v[22:23], v[22:23], v[254:255] op_sel_hi:[1,0]
	v_pk_mul_f32 v[20:21], v[20:21], v[254:255] op_sel_hi:[1,0]
	v_pk_mul_f32 v[18:19], v[18:19], v[254:255] op_sel_hi:[1,0]
	v_pk_mul_f32 v[16:17], v[16:17], v[254:255] op_sel_hi:[1,0]
	v_pk_mul_f32 v[14:15], v[14:15], v[254:255] op_sel_hi:[1,0]
	v_pk_mul_f32 v[12:13], v[12:13], v[254:255] op_sel_hi:[1,0]
	v_pk_mul_f32 v[10:11], v[10:11], v[254:255] op_sel_hi:[1,0]
	v_pk_mul_f32 v[8:9], v[8:9], v[254:255] op_sel_hi:[1,0]
	v_pk_mul_f32 v[6:7], v[6:7], v[254:255] op_sel_hi:[1,0]
	v_pk_mul_f32 v[4:5], v[4:5], v[254:255] op_sel_hi:[1,0]
	v_pk_mul_f32 v[2:3], v[2:3], v[254:255] op_sel_hi:[1,0]
	v_pk_mul_f32 v[0:1], v[0:1], v[254:255] op_sel_hi:[1,0]
	v_mul_f32_e32 v167, v167, v254
	s_branch .LswpA_back
.LswpB_resc:
	s_nop 15
	v_sub_f32_e32 v254, v194, v244
	v_exp_f32_e32 v254, v254
	s_nop 0
	v_pk_mul_f32 v[62:63], v[62:63], v[254:255] op_sel_hi:[1,0]
	v_pk_mul_f32 v[60:61], v[60:61], v[254:255] op_sel_hi:[1,0]
	v_pk_mul_f32 v[58:59], v[58:59], v[254:255] op_sel_hi:[1,0]
	v_pk_mul_f32 v[56:57], v[56:57], v[254:255] op_sel_hi:[1,0]
	v_pk_mul_f32 v[54:55], v[54:55], v[254:255] op_sel_hi:[1,0]
	v_pk_mul_f32 v[52:53], v[52:53], v[254:255] op_sel_hi:[1,0]
	v_pk_mul_f32 v[50:51], v[50:51], v[254:255] op_sel_hi:[1,0]
	v_pk_mul_f32 v[48:49], v[48:49], v[254:255] op_sel_hi:[1,0]
	v_pk_mul_f32 v[46:47], v[46:47], v[254:255] op_sel_hi:[1,0]
	v_pk_mul_f32 v[44:45], v[44:45], v[254:255] op_sel_hi:[1,0]
	v_pk_mul_f32 v[42:43], v[42:43], v[254:255] op_sel_hi:[1,0]
	v_pk_mul_f32 v[40:41], v[40:41], v[254:255] op_sel_hi:[1,0]
	v_pk_mul_f32 v[38:39], v[38:39], v[254:255] op_sel_hi:[1,0]
	v_pk_mul_f32 v[36:37], v[36:37], v[254:255] op_sel_hi:[1,0]
	v_pk_mul_f32 v[34:35], v[34:35], v[254:255] op_sel_hi:[1,0]
	v_pk_mul_f32 v[32:33], v[32:33], v[254:255] op_sel_hi:[1,0]
	v_pk_mul_f32 v[30:31], v[30:31], v[254:255] op_sel_hi:[1,0]
	v_pk_mul_f32 v[28:29], v[28:29], v[254:255] op_sel_hi:[1,0]
	v_pk_mul_f32 v[26:27], v[26:27], v[254:255] op_sel_hi:[1,0]
	v_pk_mul_f32 v[24:25], v[24:25], v[254:255] op_sel_hi:[1,0]
	v_pk_mul_f32 v[22:23], v[22:23], v[254:255] op_sel_hi:[1,0]
	v_pk_mul_f32 v[20:21], v[20:21], v[254:255] op_sel_hi:[1,0]
	v_pk_mul_f32 v[18:19], v[18:19], v[254:255] op_sel_hi:[1,0]
	v_pk_mul_f32 v[16:17], v[16:17], v[254:255] op_sel_hi:[1,0]
	v_pk_mul_f32 v[14:15], v[14:15], v[254:255] op_sel_hi:[1,0]
	v_pk_mul_f32 v[12:13], v[12:13], v[254:255] op_sel_hi:[1,0]
	v_pk_mul_f32 v[10:11], v[10:11], v[254:255] op_sel_hi:[1,0]
	v_pk_mul_f32 v[8:9], v[8:9], v[254:255] op_sel_hi:[1,0]
	v_pk_mul_f32 v[6:7], v[6:7], v[254:255] op_sel_hi:[1,0]
	v_pk_mul_f32 v[4:5], v[4:5], v[254:255] op_sel_hi:[1,0]
	v_pk_mul_f32 v[2:3], v[2:3], v[254:255] op_sel_hi:[1,0]
	v_pk_mul_f32 v[0:1], v[0:1], v[254:255] op_sel_hi:[1,0]
	v_mul_f32_e32 v167, v167, v254
	s_branch .LswpB_back
